# every seam after the preparation XCD-local (guarded): NSA units drawn from one ticket counter per workgroup class so each XCD runs its two batches end to end
# speedup vs baseline: 1.0049x; 1.0049x over previous
; __global__ void __launch_bounds__(NTHREADS, 2) fwd_kernel(Args a) {
;     ...
;         int nxt = 0; if (tid == 0) nxt = (int)__hip_atomic_fetch_add((unsigned*)(ws + NSA_Q_OFF), 1u, __ATOMIC_RELAXED, __HIP_MEMORY_SCOPE_AGENT);
.LBB0_861:
	v_mov_b32_e32 v168, 0
	v_readfirstlane_b32 s0, v214
	v_cmp_eq_u32_e64 s[2:3], 0, v214
	s_and_saveexec_b64 s[4:5], s[2:3]
	s_cbranch_execz .LBB0_865
	s_mov_b64 s[8:9], exec
	v_mbcnt_lo_u32_b32 v0, s8, 0
	v_mbcnt_hi_u32_b32 v0, s9, v0
	v_cmp_eq_u32_e32 vcc, 0, v0
	s_and_saveexec_b64 s[6:7], vcc
	s_cbranch_execz .LBB0_864
	s_bcnt1_i32_b64 s1, s[8:9]
	s_waitcnt lgkmcnt(0)
	v_mov_b32_e32 v1, s33
	v_and_b32_e32 v1, 7, v1
	v_lshlrev_b32_e32 v1, 8, v1
	v_add_u32_e32 v1, 0x8000, v1
	v_mov_b32_e32 v2, s1
	global_atomic_add v1, v1, v2, s[40:41] sc0

; __global__ void __launch_bounds__(NTHREADS, 2) fwd_kernel(Args a) {
;     ...
;         if (tid < 32) { unsigned sp = 0; while (__hip_atomic_load((unsigned*)(ws + CMP_CNT_OFF) + 64 * tid, __ATOMIC_RELAXED, __HIP_MEMORY_SCOPE_AGENT) < 8u) { __builtin_amdgcn_s_sleep(2); if (++sp > (1u << 22)) break; } }
.LBB0_870:
	s_or_b64 exec, exec, s[4:5]
	v_cmp_gt_i32_e32 vcc, 32, v214
	s_waitcnt lgkmcnt(0)
	s_barrier
	s_and_saveexec_b64 s[4:5], vcc
	s_cbranch_execz .LBB0_883
	v_and_b32_e32 v0, 3, v214
	v_mov_b32_e32 v1, s33
	v_and_b32_e32 v1, 7, v1
	v_lshl_add_u32 v0, v1, 2, v0
	v_lshlrev_b32_e32 v0, 6, v0
	v_ashrrev_i32_e32 v1, 31, v0
	v_lshl_add_u64 v[0:1], v[0:1], 2, s[40:41]
	s_mov_b64 s[6:7], 0x5000
	v_lshl_add_u64 v[0:1], v[0:1], 0, s[6:7]
	s_mov_b32 s1, 0x400001
	s_mov_b64 s[6:7], 0
	s_branch .LBB0_877

; #define LAS __attribute__((address_space(3)))
; __device__ __forceinline__ void nsa_unit(int b, int g, int tq, const Args& a, LAS unsigned char* lds, int tid, int wave, int lane, int& nxt) {
;     unsigned char* ws = a.ws;
;     const bf16_t* QA = (const bf16_t*)(ws + WS_A + A_QA);
;     const bf16_t* KS = (const bf16_t*)(ws + WS_A + A_KS); const bf16_t* VS = (const bf16_t*)(ws + WS_A + A_VS);
;     const bf16_t* KW = (const bf16_t*)(ws + WS_A + A_KW); const bf16_t* VW = (const bf16_t*)(ws + WS_A + A_VW);
;     const bf16_t* KCM = (const bf16_t*)(ws + WS_KCMP) + (size_t)(b * 2 + g) * 128 * 64; const bf16_t* VCM = (const bf16_t*)(ws + WS_VCMP) + (size_t)(b * 2 + g) * 128 * 64;
;     const float* GA = (const float*)(ws + WS_GA); bf16_t* ON = (bf16_t*)(ws + WS_OC);
;     LAS unsigned char* cmpb = lds + NL_CMP;
;     LAS float* imp = (LAS float*)(lds + NL_IMP);
;     LAS unsigned* selm = (LAS unsigned*)(lds + NL_SEL); LAS unsigned* uni = (LAS unsigned*)(lds + NL_UNI);
;     const int hr = wave >> 1, th = wave & 1, head = 4 * g + hr, h = lane >> 5, tl = 32 * th + (lane & 31), t = 64 * tq + tl;
;     const size_t row = (size_t)b * SEQ + t;
;     LAS const float* tabh = (LAS const float*)(lds + NL_TAB) + 320 * head;
;     static_assert(A_KW - A_KS == A_VW - A_VS, "window K/V sit at one common offset from the selected K/V");
;     const int wv = __builtin_amdgcn_readfirstlane(tid >> 6);
;     const char* ksrc = (const char*)(KS + (size_t)b * SEQ * 128 + 64 * g) + ((size_t)(8 * wv + (lane >> 3)) * 128 + (((lane & 7) ^ (lane >> 3)) * 8)) * 2;
;     const char* vsrc = (const char*)(VS + (size_t)b * SEQ * 128 + 64 * g) + ((size_t)(8 * wv + (lane >> 3)) * 128 + (((lane & 7) ^ (4 * ((lane >> 4) & 1))) * 8)) * 2;
;     const unsigned kvb0 = (unsigned)(uintptr_t)lds;
.LBB0_883:
	s_or_b64 exec, exec, s[4:5]
	v_writelane_b32 v248, s90, 5
	s_load_dwordx2 s[4:5], s[90:91], 0xc8
	s_mov_b32 s45, 0
	v_writelane_b32 v248, s91, 6
	v_mov_b32_e32 v1, 0
	s_movk_i32 s80, 0x90
	s_waitcnt lgkmcnt(0)
	s_add_u32 s46, s4, 0x7a00000
	s_addc_u32 s47, s5, 0
	s_add_u32 s68, s4, 0xaa00000
	s_addc_u32 s69, s5, 0
	s_add_u32 s70, s4, 0xb200000
	s_addc_u32 s71, s5, 0
	s_add_u32 s72, s4, 0x3300000
	s_addc_u32 s73, s5, 0
	s_add_u32 s74, s4, 0x3380000
	s_addc_u32 s75, s5, 0
	s_add_u32 s48, s4, 0x3600000
	s_addc_u32 s49, s5, 0
	s_ashr_i32 s76, s0, 7
	s_lshr_b32 s0, s0, 1
	s_and_b32 s77, s0, 32
	s_add_u32 s0, s4, 0x8000
	s_addc_u32 s1, s5, 0
	s_and_b32 s78, s33, 7
	s_lshl_b32 s78, s78, 8
	s_add_u32 s0, s0, s78
	s_addc_u32 s1, s1, 0
	s_lshl_b32 s78, s76, 6
	s_add_u32 s52, s4, 0x1aa00000
	s_addc_u32 s53, s5, 0
	s_add_i32 s79, 0, 0x1d508
	v_writelane_b32 v248, s0, 1
	v_mov_b32_e32 v169, s79
	s_add_i32 s81, 0, 0x10800
	s_add_i32 s82, 0, 0x12c00
	s_add_i32 s83, 0, 0x1d500
	s_add_i32 s84, 0, 0x15000
	s_movk_i32 s85, 0x84
	s_movk_i32 s86, 0x1ff
	s_mov_b32 s55, 0xe0ad78ec
	s_mov_b32 s88, 0xff61b1e6
	s_movk_i32 s89, 0x200
	s_movk_i32 s90, 0x220
	s_mov_b32 s91, 0x41f00000
	v_mov_b32_e32 v170, 0x7f
	v_mov_b32_e32 v171, 0x27f
	v_mov_b32_e32 v172, 0xff61b1e6
	v_mov_b32_e32 v173, 0xf149f2ca
	v_writelane_b32 v248, s1, 2
	s_branch .LBB0_886

; #define LAS __attribute__((address_space(3)))
; template <int MODE> __device__ __forceinline__ int pop_tile(unsigned& tiles) { int j; if (MODE == 2) { j = 31 - __builtin_clz(tiles); tiles &= ~(1u << j); } else { j = __builtin_ctz(tiles); tiles &= tiles - 1u; } return j; }
; __device__ __forceinline__ void nsa_unit(int b, int g, int tq, const Args& a, LAS unsigned char* lds, int tid, int wave, int lane, int& nxt) {
;     ...
;     const int wv = __builtin_amdgcn_readfirstlane(tid >> 6);
;     const char* ksrc = (const char*)(KS + (size_t)b * SEQ * 128 + 64 * g) + ((size_t)(8 * wv + (lane >> 3)) * 128 + (((lane & 7) ^ (lane >> 3)) * 8)) * 2;
;     const char* vsrc = (const char*)(VS + (size_t)b * SEQ * 128 + 64 * g) + ((size_t)(8 * wv + (lane >> 3)) * 128 + (((lane & 7) ^ (4 * ((lane >> 4) & 1))) * 8)) * 2;
;     const unsigned kvb0 = (unsigned)(uintptr_t)lds;
;     ...
;     unsigned wt; { const int jlo = max(tq - 8, 0); const unsigned hi = (tq == 31) ? 0xffffffffu : ((1u << (tq + 1)) - 1u); wt = hi & ~((1u << jlo) - 1u); }
;     int j0 = pop_tile<2>(wt), m0 = 2, j1 = -1, m1 = 2;
;     NL_DMA(2, j0, 0);
;     if (wt) { j1 = pop_tile<2>(wt); NL_DMA(2, j1, FBUF); }
; __global__ void __launch_bounds__(NTHREADS, 2) fwd_kernel(Args a) {
;     ...
;         for (;;) {
;             volatile LAS int* tick = (volatile LAS int*)(lds + NL_UNI + 8);
;             if (tid == 0) tick[0] = nxt;
;             asm volatile("s_waitcnt lgkmcnt(0)" ::: "memory"); __builtin_amdgcn_s_barrier(); asm volatile("" ::: "memory");
;             const int tk = __builtin_amdgcn_readfirstlane(tick[0]);
;             if (tk >= 1024) break;
;             const int tq = 31 - (tk >> 5), bg = tk & 31;
;             int tu = tid; asm volatile("" : "+v"(tu)); nsa_unit(bg >> 1, bg & 1, tq, a, lds, tu, wave, tu & 63, nxt); }
.LBB0_886:
	s_and_saveexec_b64 s[4:5], s[2:3]
	v_mov_b32_e32 v0, s79
	ds_write_b32 v0, v168
	s_or_b64 exec, exec, s[4:5]
	s_waitcnt lgkmcnt(0)
	s_barrier
	ds_read_b32 v0, v169
	s_waitcnt lgkmcnt(0)
	v_readfirstlane_b32 s4, v0
	s_lshr_b32 s0, s4, 2
	s_lshl_b32 s0, s0, 5
	s_and_b32 s1, s4, 3
	s_or_b32 s0, s0, s1
	s_and_b32 s1, s33, 7
	s_lshl_b32 s1, s1, 2
	s_or_b32 s0, s0, s1
	s_cmpk_gt_i32 s4, 0x7f
	s_cselect_b32 s4, 0x400, s0
	s_cmpk_gt_i32 s4, 0x3ff
	s_cselect_b64 s[56:57], -1, 0
	s_and_b64 vcc, exec, s[56:57]
	s_cbranch_vccnz .LBB0_885
	v_mov_b32_e32 v86, v214
	s_ashr_i32 s67, s4, 5
	s_bfe_u32 s0, s4, 0x40001
	v_readfirstlane_b32 s5, v86
	s_sub_i32 s38, 31, s67
	s_and_b32 s1, s4, 1
	s_ashr_i32 s5, s5, 6
	s_lshl_b32 s8, s0, 19
	v_bfe_u32 v34, v86, 3, 3
	s_add_u32 s6, s68, s8
	v_lshl_or_b32 v2, s5, 3, v34
	s_addc_u32 s7, s69, 0
	s_lshl_b32 s9, s1, 7
	v_ashrrev_i32_e32 v3, 31, v2
	s_add_u32 s6, s6, s9
	v_lshlrev_b64 v[2:3], 7, v[2:3]
	v_bitop3_b32 v0, v34, v86, 7 bitop3:0x78
	s_addc_u32 s7, s7, 0
	v_lshl_or_b32 v4, v0, 3, v2
	v_mov_b32_e32 v5, v3
	v_lshl_add_u64 v[160:161], v[4:5], 1, s[6:7]
	s_add_u32 s6, s70, s8
	v_and_b32_e32 v82, 7, v86
	s_addc_u32 s7, s71, 0
	v_bfe_u32 v35, v86, 2, 4
	s_add_u32 s6, s6, s9
	v_bitop3_b32 v0, v35, v82, 4 bitop3:0x6c
	s_addc_u32 s7, s7, 0
	v_lshl_or_b32 v2, v0, 3, v2
	v_lshl_add_u64 v[162:163], v[2:3], 1, s[6:7]
	s_lshl_b32 s6, 2, s38
	v_sub_u32_e64 v0, s38, 8 clamp
	s_add_i32 s6, s6, -1
	s_cmp_gt_u32 s4, 31
	v_readfirstlane_b32 s4, v0
	s_cselect_b32 s15, s6, -1
	s_lshl_b32 s4, -1, s4
	s_and_b32 s4, s15, s4
	s_flbit_i32_b32 s6, s4
	s_xor_b32 s14, s6, 31
	s_lshl_b32 s6, 1, s14
	s_andn2_b32 s4, s4, s6
	s_lshl_b32 s6, s14, 14
	s_or_b32 s44, s6, 0x1000000
	s_lshl_b32 s94, s5, 10
	v_lshl_add_u64 v[2:3], v[160:161], 0, s[44:45]
	s_add_i32 s94, s94, 0
	s_mov_b32 m0, s94
	s_nop 0
	global_load_lds_dwordx4 v[2:3], off
	v_lshl_add_u64 v[2:3], v[162:163], 0, s[44:45]
	s_add_i32 s95, s94, 0x2000
	s_mov_b32 m0, s95
	s_nop 0
	global_load_lds_dwordx4 v[2:3], off
	s_mov_b32 s97, -1
	s_cmp_eq_u32 s4, 0
	s_mov_b32 s39, 0
	s_cbranch_scc1 .LBB0_891
	s_flbit_i32_b32 s5, s4
	s_xor_b32 s97, s5, 31
	s_lshl_b32 s5, 1, s97
	s_andn2_b32 s39, s4, s5
	s_lshl_b32 s4, s97, 14
	s_or_b32 s44, s4, 0x1000000
	v_lshl_add_u64 v[2:3], v[160:161], 0, s[44:45]
	s_add_i32 s4, s94, 0x4000
	s_mov_b32 m0, s4
	s_nop 0
	global_load_lds_dwordx4 v[2:3], off
	v_lshl_add_u64 v[2:3], v[162:163], 0, s[44:45]
	s_add_i32 s4, s94, 0x6000
	s_mov_b32 m0, s4
	s_nop 0
	global_load_lds_dwordx4 v[2:3], off

; __device__ __forceinline__ unsigned xb_ld(unsigned* p)              { return __hip_atomic_load(p, __ATOMIC_RELAXED, __HIP_MEMORY_SCOPE_AGENT); }
; __device__ __forceinline__ unsigned xb_add(unsigned* p, unsigned v) { return __hip_atomic_fetch_add(p, v, __ATOMIC_RELAXED, __HIP_MEMORY_SCOPE_AGENT); }
; #define XB_SPIN(cond, bar) do { unsigned _sp = 0; while (cond) { __builtin_amdgcn_s_sleep(1); \
;     if ((++_sp & 255u) == 0u) { if (xb_ld(&(bar)[XB_TMO])) break; if (_sp > XB_SPIN_CAP) { atomicAdd(&(bar)[XB_TMO], 1u); break; } } } } while (0)
; __device__ __forceinline__ void xcd_barrier(const XcdBarrier& b, int tid) {
;     ...
;         const unsigned old = xb_add(&bar[XB_XSUB(b.x)], 1u);
;         const unsigned gen = old / nloc;
;         if (old + 1u == (gen + 1u) * nloc) {
;             __builtin_amdgcn_fence(__ATOMIC_RELEASE, "agent");
;             asm volatile("s_waitcnt vmcnt(0)" ::: "memory");
;             const unsigned og = xb_add(&bar[XB_TOP], 1u);
;             const unsigned tg = og / nx;
;             if (og + 1u == (tg + 1u) * nx) xb_add(&bar[XB_TOPGEN], 1u);
;             else XB_SPIN(xb_ld(&bar[XB_TOPGEN]) == tg, bar);
;             __builtin_amdgcn_fence(__ATOMIC_ACQUIRE, "agent");
;             xb_add(&bar[XB_XGEN(b.x)], 1u);
.LBB0_1023:
	s_andn2_saveexec_b64 s[0:1], s[6:7]
	s_cbranch_execz .LBB0_1043
	s_mov_b64 s[6:7], exec
	v_readlane_b32 s0, v248, 32
	s_nop 3
	s_cmp_eq_u32 s0, 1
	s_cbranch_scc1 .LBB0_1040
	buffer_wbl2 sc1
	s_waitcnt lgkmcnt(0)
	s_waitcnt vmcnt(0)
	v_mbcnt_lo_u32_b32 v1, s6, 0
	v_mbcnt_hi_u32_b32 v1, s7, v1
	v_cmp_eq_u32_e32 vcc, 0, v1
	s_and_saveexec_b64 s[8:9], vcc
	s_cbranch_execz .LBB0_1026
	s_bcnt1_i32_b64 s0, s[6:7]
	v_mov_b32_e32 v2, 0x3000
	v_mov_b32_e32 v3, s0
	global_atomic_add v2, v2, v3, s[40:41] offset:1024 sc0
